# plus: routed-unit member scan prefetches its eight selection vectors; static s_setprio 1 for waves 4-7 in forgetting attention
# baseline (speedup 1.0000x reference)
; __device__ __forceinline__ float bf2f(short s) { return __uint_as_float(((unsigned)(unsigned short)s) << 16); }
; #define LOADT(i, kreg, vreg, creg) do { const int k0_ = KEY0(i); kreg = *(const u32x4*)(A.K + (size_t)(k0_ + lane) * A.ldkv + wid * 8); vreg = *(const u32x4*)(A.V + (size_t)(k0_ + lane) * A.ldkv + wid * 8); \
;         if (MODE == M_FOX) { if (tid < 64) creg = A.cf[k0_ + tid] * LOG2E; } } while (0)
; template <int MODE>
; __device__ __forceinline__ void attn_unit(LAS unsigned char* lds, const AttnArgs& A, int qb) {
;     int tid_ = threadIdx.x; asm volatile("" : "+v"(tid_)); const int tid = tid_, lane = tid & 63, wid = __builtin_amdgcn_readfirstlane(tid >> 6), r32 = lane & 31, hi = lane >> 5;
;     const int q0 = qb * 256, w0 = q0 + wid * 32, row = w0 + r32;
;     bf16x8 qr[4];
; #pragma unroll
;     for (int d0 = 0; d0 < 4; ++d0) qr[d0] = *(const bf16x8*)(A.Q + (size_t)row * A.ldq + d0 * 16 + hi * 8);
;     ...
;     if (MODE == M_FOX) {
;         float s = 0.f;
; #pragma unroll
;         for (int d0 = 0; d0 < 4; ++d0)
; #pragma unroll
;             for (int e = 0; e < 8; ++e) { const float x = bf2f(qr[d0][e]); s += x * x; }
;         s += __shfl_xor(s, 32);
;         qb2 = sqrtf(s * A.kmax2) * C2 * 1.01f;
;         cq2 = A.cf[row] * LOG2E;
;     }
;     const int NT = (MODE == M_XA || MODE == M_MOBA) ? 4 : (q0 / 64 + 4);
;     f32x16 o0, o1;
; #pragma unroll
;     for (int r = 0; r < 16; ++r) { o0[r] = 0.f; o1[r] = 0.f; }
;     float m_run = -1e30f, l_run = 0.f, T = 0.f;
;     u32x4 k1 = (u32x4){0u, 0u, 0u, 0u}, v1 = k1, k2 = k1, v2 = k1, k3 = k1, v3 = k1; float c1 = 0.f, c2 = 0.f, c3 = 0.f;
;     ...
;     LOADT(0, k1, v1, c1); if (NT > 1) LOADT(1, k2, v2, c2); if (NT > 2) LOADT(2, k3, v3, c3);
.LBB0_954:
	s_lshl_b32 s80, s1, 6
	s_andn2_b32 s0, 63, s0
	s_lshl_b64 s[20:21], s[80:81], 1
	s_add_u32 s2, s30, s20
	s_addc_u32 s3, s31, s21
	s_add_u32 s4, s14, s20
	s_addc_u32 s5, s15, s21
	s_add_u32 s8, s16, s20
	s_addc_u32 s9, s17, s21
	s_lshl_b32 s1, s1, 16
	v_mov_b32_e32 v2, v216
	s_add_u32 s22, s36, s1
	s_addc_u32 s23, s37, 0
	v_readfirstlane_b32 s6, v2
	s_ashr_i32 s42, s6, 6
	s_cmp_lt_u32 s42, 4
	s_cbranch_scc1 .Lfox_prio_skip
	s_setprio 1
.Lfox_prio_skip:
	s_lshl_b32 s80, s0, 8
	s_lshl_b32 s43, s42, 5
	v_and_b32_e32 v8, 31, v2
	s_add_i32 s43, s43, s80
	v_or_b32_e32 v154, s43, v8
	v_ashrrev_i32_e32 v155, 31, v154
	v_bfe_u32 v7, v2, 5, 1
	v_lshlrev_b64 v[4:5], 11, v[154:155]
	v_lshl_add_u64 v[4:5], s[2:3], 0, v[4:5]
	v_lshlrev_b32_e32 v0, 4, v7
	v_lshl_add_u64 v[4:5], v[4:5], 0, v[0:1]
	global_load_dwordx4 v[98:101], v[4:5], off
	global_load_dwordx4 v[102:105], v[4:5], off offset:32
	global_load_dwordx4 v[106:109], v[4:5], off offset:64
	global_load_dwordx4 v[110:113], v[4:5], off offset:96
	v_and_b32_e32 v6, 63, v2
	s_lshl_b32 s2, s42, 3
	s_ashr_i32 s3, s2, 31
	s_lshl_b64 s[10:11], s[2:3], 1
	v_cmp_gt_i32_e64 s[6:7], 64, v2
	s_waitcnt vmcnt(3)
	v_and_b32_e32 v4, 0xffff0000, v98
	v_lshlrev_b32_e32 v3, 16, v98
	v_mul_f32_e32 v10, v4, v4
	v_fmac_f32_e32 v10, v3, v3
	v_lshlrev_b32_e32 v3, 16, v99
	v_fmac_f32_e32 v10, v3, v3
	v_and_b32_e32 v3, 0xffff0000, v99
	v_fmac_f32_e32 v10, v3, v3
	v_lshlrev_b32_e32 v3, 16, v100
	v_fmac_f32_e32 v10, v3, v3
	v_and_b32_e32 v3, 0xffff0000, v100
	v_fmac_f32_e32 v10, v3, v3
	v_lshlrev_b32_e32 v3, 16, v101
	v_fmac_f32_e32 v10, v3, v3
	v_and_b32_e32 v3, 0xffff0000, v101
	v_fmac_f32_e32 v10, v3, v3
	s_waitcnt vmcnt(2)
	v_lshlrev_b32_e32 v3, 16, v102
	v_fmac_f32_e32 v10, v3, v3
	v_and_b32_e32 v3, 0xffff0000, v102
	v_fmac_f32_e32 v10, v3, v3
	v_lshlrev_b32_e32 v3, 16, v103
	v_fmac_f32_e32 v10, v3, v3
	v_and_b32_e32 v3, 0xffff0000, v103
	v_fmac_f32_e32 v10, v3, v3
	v_lshlrev_b32_e32 v3, 16, v104
	v_fmac_f32_e32 v10, v3, v3
	v_and_b32_e32 v3, 0xffff0000, v104
	v_fmac_f32_e32 v10, v3, v3
	v_lshlrev_b32_e32 v3, 16, v105
	v_fmac_f32_e32 v10, v3, v3
	v_and_b32_e32 v3, 0xffff0000, v105
	v_fmac_f32_e32 v10, v3, v3
	s_waitcnt vmcnt(1)
	v_lshlrev_b32_e32 v3, 16, v106
	v_fmac_f32_e32 v10, v3, v3
	v_and_b32_e32 v3, 0xffff0000, v106
	v_fmac_f32_e32 v10, v3, v3
	v_lshlrev_b32_e32 v3, 16, v107
	v_fmac_f32_e32 v10, v3, v3
	v_and_b32_e32 v3, 0xffff0000, v107
	v_fmac_f32_e32 v10, v3, v3
	v_lshlrev_b32_e32 v3, 16, v108
	v_fmac_f32_e32 v10, v3, v3
	v_and_b32_e32 v3, 0xffff0000, v108
	v_fmac_f32_e32 v10, v3, v3
	v_lshlrev_b32_e32 v3, 16, v109
	v_fmac_f32_e32 v10, v3, v3
	v_and_b32_e32 v3, 0xffff0000, v109
	v_fmac_f32_e32 v10, v3, v3
	s_waitcnt vmcnt(0)
	v_lshlrev_b32_e32 v3, 16, v110
	v_fmac_f32_e32 v10, v3, v3
	v_and_b32_e32 v3, 0xffff0000, v110
	v_fmac_f32_e32 v10, v3, v3
	v_lshlrev_b32_e32 v3, 16, v111
	v_fmac_f32_e32 v10, v3, v3
	v_and_b32_e32 v3, 0xffff0000, v111
	v_fmac_f32_e32 v10, v3, v3
	v_lshlrev_b32_e32 v3, 16, v112
	v_fmac_f32_e32 v10, v3, v3
	v_and_b32_e32 v3, 0xffff0000, v112
	v_fmac_f32_e32 v10, v3, v3
	v_lshlrev_b32_e32 v3, 16, v113
	v_fmac_f32_e32 v10, v3, v3
	v_and_b32_e32 v3, 0xffff0000, v113
	v_and_b32_e32 v4, 64, v223
	v_fmac_f32_e32 v10, v3, v3
	v_xor_b32_e32 v3, 32, v223
	v_add_u32_e32 v4, 64, v4
	v_cmp_lt_i32_e32 vcc, v3, v4
	v_lshl_add_u64 v[4:5], v[154:155], 2, s[22:23]
	global_load_dword v11, v[4:5], off
	v_cndmask_b32_e32 v3, v223, v3, vcc
	v_lshlrev_b32_e32 v176, 2, v3
	v_or_b32_e32 v3, s80, v6
	v_mov_b32_e32 v4, 0x60000
	v_lshl_or_b32 v4, v3, 11, v4
	v_mov_b32_e32 v5, v1
	v_lshl_add_u64 v[14:15], s[4:5], 0, v[4:5]
	v_lshl_add_u64 v[4:5], s[8:9], 0, v[4:5]
	v_lshl_add_u64 v[14:15], v[14:15], 0, s[10:11]
	v_lshl_add_u64 v[4:5], v[4:5], 0, s[10:11]
	global_load_dwordx4 v[114:117], v[14:15], off
	global_load_dwordx4 v[118:121], v[4:5], off
	ds_bpermute_b32 v12, v176, v10
	v_ashrrev_i32_e32 v3, 31, v2
	s_and_saveexec_b64 s[24:25], s[6:7]
	s_cbranch_execz .LBB0_956
	v_lshl_add_u64 v[4:5], v[2:3], 0, s[80:81]
	v_lshl_add_u64 v[4:5], v[4:5], 2, s[22:23]
	global_load_dword v4, v[4:5], off offset:768
	s_waitcnt vmcnt(0)
	v_mul_f32_e32 v157, 0x3fb8aa3b, v4

; #define WSP(T, off) ((T*)wsoff(off))
; __device__ __forceinline__ void moba_routed_unit(LAS unsigned char* lds, const bf16_t* Qh, const bf16_t* Kh, const bf16_t* Vh, const int* selh, bf16_t* parth, float* lseh, int j, int b0, int b1) {
;     ...
;     if (tid == 0) *cnt = 0;
;     u32x4 kk[4], vv[4];
; #pragma unroll
;     for (int tl = 0; tl < 4; ++tl) { const size_t ro = (size_t)(256 * j + 64 * tl + lane) * 1024 + wid * 8; kk[tl] = *(const u32x4*)(Kh + ro); vv[tl] = *(const u32x4*)(Vh + ro); }
;     __syncthreads();
;     typedef int i32x4 __attribute__((ext_vector_type(4)));
;     for (int t = 256 * b0 + tid; t < 256 * b1; t += 512) {
;         const i32x4 s = *(const i32x4*)(selh + (size_t)t * 4);
; __global__ void __launch_bounds__(512, 2) fwd_kernel(Args args) {
;     ...
;                     const int h8 = idx & 7; int u = idx >> 3, j = 0;
;                     while (u >= ((63 - j + 15) >> 4)) { u -= ((63 - j + 15) >> 4); ++j; }
;                     const int b0 = j + 1 + 16 * u, b1 = (b0 + 16 < 64) ? b0 + 16 : 64;
;                     att::moba_routed_unit(lds, WSP(bf16_t, WS_Q) + (8 + h8) * 64, WSP(bf16_t, WS_K) + (8 + h8) * 64, WSP(bf16_t, WS_V) + (8 + h8) * 64, WSP(int, WS_SEL) + (size_t)h8 * S * 4,
;                                           (bf16_t*)OUTP + h8 * 4 * 64, WSP(float, WS_LSE) + h8 * 4, j, b0, b1);
.LBB0_1287:
	s_or_b64 exec, exec, s[26:27]
	s_and_b32 s2, s0, 7
	s_lshl_b32 s0, s3, 4
	s_load_dwordx2 s[26:27], s[8:9], 0x0
	s_load_dwordx2 s[30:31], s[22:23], 0x0
	s_nop 0
	s_load_dwordx2 s[8:9], s[24:25], 0x0
	s_add_i32 s3, s1, s0
	s_add_i32 s3, s3, 1
	s_min_i32 s22, s3, 48
	s_waitcnt lgkmcnt(0)
	s_add_u32 s0, s26, s18
	s_addc_u32 s19, s27, s19
	s_lshl_b32 s23, s2, 7
	s_add_u32 s18, s0, s23
	s_addc_u32 s19, s19, 0
	s_add_u32 s0, s30, s20
	s_addc_u32 s21, s31, s21
	s_add_u32 s20, s0, s23
	s_addc_u32 s21, s21, 0
	v_and_b32_e32 v43, 63, v42
	s_ashr_i32 s0, s28, 6
	v_lshl_or_b32 v0, s1, 8, v43
	s_lshl_b32 s24, s0, 3
	s_ashr_i32 s25, s24, 31
	v_lshlrev_b64 v[2:3], 10, v[0:1]
	v_lshl_add_u64 v[2:3], v[2:3], 0, s[24:25]
	v_lshlrev_b64 v[2:3], 1, v[2:3]
	v_lshl_add_u64 v[4:5], s[18:19], 0, v[2:3]
	v_lshl_add_u64 v[2:3], s[20:21], 0, v[2:3]
	global_load_dwordx4 v[6:9], v[2:3], off offset:1024
	v_or_b32_e32 v2, 64, v0
	v_mov_b32_e32 v3, v1
	v_lshlrev_b64 v[2:3], 10, v[2:3]
	v_lshl_add_u64 v[2:3], v[2:3], 0, s[24:25]
	v_lshlrev_b64 v[2:3], 1, v[2:3]
	global_load_dwordx4 v[30:33], v[4:5], off offset:1024
	v_lshl_add_u64 v[4:5], s[18:19], 0, v[2:3]
	v_lshl_add_u64 v[2:3], s[20:21], 0, v[2:3]
	global_load_dwordx4 v[10:13], v[2:3], off offset:1024
	v_or_b32_e32 v2, 0x80, v0
	v_mov_b32_e32 v3, v1
	v_lshlrev_b64 v[2:3], 10, v[2:3]
	v_lshl_add_u64 v[2:3], v[2:3], 0, s[24:25]
	v_lshlrev_b64 v[2:3], 1, v[2:3]
	global_load_dwordx4 v[22:25], v[4:5], off offset:1024
	v_lshl_add_u64 v[4:5], s[18:19], 0, v[2:3]
	v_lshl_add_u64 v[2:3], s[20:21], 0, v[2:3]
	v_or_b32_e32 v0, 0xc0, v0
	global_load_dwordx4 v[14:17], v[2:3], off offset:1024
	v_lshlrev_b64 v[2:3], 10, v[0:1]
	v_lshl_add_u64 v[2:3], v[2:3], 0, s[24:25]
	v_lshlrev_b64 v[2:3], 1, v[2:3]
	global_load_dwordx4 v[26:29], v[4:5], off offset:1024
	v_lshl_add_u64 v[4:5], s[18:19], 0, v[2:3]
	v_lshl_add_u64 v[2:3], s[20:21], 0, v[2:3]
	global_load_dwordx4 v[18:21], v[4:5], off offset:1024
	v_lshl_add_u32 v38, s3, 8, v42
	global_load_dwordx4 v[2:5], v[2:3], off offset:1024
	s_load_dwordx2 s[14:15], s[14:15], 0x0
	s_nop 0
	s_load_dwordx2 s[16:17], s[16:17], 0x0
	s_lshl_b32 s3, s22, 8
	s_addk_i32 s3, 0x1000
	v_cmp_gt_i32_e32 vcc, s3, v38
	s_waitcnt lgkmcnt(0)
	s_barrier
	s_and_saveexec_b64 s[18:19], vcc
	s_cbranch_execz .LBB0_1302
	s_load_dwordx2 s[12:13], s[12:13], 0x0
	s_lshl_b32 s20, s2, 18
	s_add_u32 s10, s10, s20
	s_addc_u32 s11, s11, 0
	v_ashrrev_i32_e32 v39, 31, v38
	s_waitcnt lgkmcnt(0)
	s_add_u32 s10, s12, s10
	s_addc_u32 s11, s13, s11
	v_lshl_add_u64 v[40:41], v[38:39], 4, s[10:11]
	s_mov_b64 s[100:101], 0x2000
	global_load_dwordx4 v[120:123], v[40:41], off
	v_lshl_add_u64 v[152:153], v[40:41], 0, s[100:101]
	global_load_dwordx4 v[124:127], v[152:153], off
	v_lshl_add_u64 v[152:153], v[152:153], 0, s[100:101]
	global_load_dwordx4 v[128:131], v[152:153], off
	v_lshl_add_u64 v[152:153], v[152:153], 0, s[100:101]
	global_load_dwordx4 v[132:135], v[152:153], off
	v_lshl_add_u64 v[152:153], v[152:153], 0, s[100:101]
	global_load_dwordx4 v[136:139], v[152:153], off
	v_lshl_add_u64 v[152:153], v[152:153], 0, s[100:101]
	global_load_dwordx4 v[140:143], v[152:153], off
	v_lshl_add_u64 v[152:153], v[152:153], 0, s[100:101]
	global_load_dwordx4 v[144:147], v[152:153], off
	v_lshl_add_u64 v[152:153], v[152:153], 0, s[100:101]
	global_load_dwordx4 v[148:151], v[152:153], off
	s_mov_b64 s[10:11], 0
	s_branch .LBB0_1291

; __device__ __forceinline__ void moba_routed_unit(LAS unsigned char* lds, const bf16_t* Qh, const bf16_t* Kh, const bf16_t* Vh, const int* selh, bf16_t* parth, float* lseh, int j, int b0, int b1) {
;     ...
;     for (int t = 256 * b0 + tid; t < 256 * b1; t += 512) {
;         const i32x4 s = *(const i32x4*)(selh + (size_t)t * 4);
;         if (s.x == j) { const int p = __hip_atomic_fetch_add(cnt, 1, __ATOMIC_RELAXED, __HIP_MEMORY_SCOPE_WORKGROUP); list[p] = t; }
;         if (s.y == j) { const int p = __hip_atomic_fetch_add(cnt, 1, __ATOMIC_RELAXED, __HIP_MEMORY_SCOPE_WORKGROUP); list[p] = t | (1 << 16); }
.LBB0_1291:
	s_waitcnt vmcnt(0)
	v_mov_b64_e32 v[34:35], v[120:121]
	v_mov_b64_e32 v[36:37], v[122:123]
	v_mov_b64_e32 v[120:121], v[124:125]
	v_mov_b64_e32 v[122:123], v[126:127]
	v_mov_b64_e32 v[124:125], v[128:129]
	v_mov_b64_e32 v[126:127], v[130:131]
	v_mov_b64_e32 v[128:129], v[132:133]
	v_mov_b64_e32 v[130:131], v[134:135]
	v_mov_b64_e32 v[132:133], v[136:137]
	v_mov_b64_e32 v[134:135], v[138:139]
	v_mov_b64_e32 v[136:137], v[140:141]
	v_mov_b64_e32 v[138:139], v[142:143]
	v_mov_b64_e32 v[140:141], v[144:145]
	v_mov_b64_e32 v[142:143], v[146:147]
	v_mov_b64_e32 v[144:145], v[148:149]
	v_mov_b64_e32 v[146:147], v[150:151]
	v_cmp_eq_u32_e32 vcc, s1, v34
	s_and_saveexec_b64 s[12:13], vcc
	s_cbranch_execz .LBB0_1296
	s_mov_b64 s[22:23], exec
	v_mbcnt_lo_u32_b32 v0, s22, 0
	v_mbcnt_hi_u32_b32 v0, s23, v0
	v_cmp_eq_u32_e32 vcc, 0, v0
	s_and_saveexec_b64 s[20:21], vcc
	s_cbranch_execz .LBB0_1294
	s_bcnt1_i32_b64 s22, s[22:23]
	v_readlane_b32 s23, v255, 9
	v_mov_b32_e32 v37, s22
	s_nop 0
	v_mov_b32_e32 v34, s23
	ds_add_rtn_u32 v34, v34, v37
